# prompt attention fast path with staggered wave halves and scalar f32 adds; down-GEMM units remapped to 4 row panels x 8 column tiles per XCD round
# speedup vs baseline: 1.0073x; 1.0073x over previous
_Z10fwd_kernel4Args:
	s_mov_b32 s101, 0
	s_load_dword s33, s[0:1], 0xf8
	v_writelane_b32 v254, s2, 0
	s_add_u32 s2, s0, 0xf8
	v_writelane_b32 v254, s0, 1
	s_addc_u32 s3, s1, 0
	v_lshl_add_u32 v1, v0, 2, 0
	v_writelane_b32 v254, s1, 2
	v_writelane_b32 v254, s2, 3
	v_add_u32_e32 v1, 0x20000, v1
	v_mov_b32_e32 v2, 0
	v_writelane_b32 v254, s3, 4
	ds_write2st64_b32 v1, v2, v2 offset1:8
	ds_write2st64_b32 v1, v2, v2 offset0:16 offset1:24
	v_or_b32_e32 v1, 0x800, v0
	s_mov_b64 s[0:1], -1
	s_and_saveexec_b64 s[2:3], s[0:1]
	v_lshl_add_u32 v3, v1, 2, 0
	v_add_u32_e32 v3, 0x20000, v3
	ds_write_b32 v3, v2
	s_or_b64 exec, exec, s[2:3]
	s_and_saveexec_b64 s[2:3], s[0:1]
	s_add_i32 s0, 0, 0x20000
	v_lshl_add_u32 v1, v1, 2, s0
	v_mov_b32_e32 v2, 0
	ds_write_b32 v1, v2 offset:2048
	s_or_b64 exec, exec, s[2:3]
	v_readlane_b32 s0, v254, 1
	v_readlane_b32 s1, v254, 2
	s_load_dwordx4 s[48:51], s[0:1], 0xe8
	v_or_b32_e32 v1, 0xc00, v0
	v_cmp_gt_u32_e64 s[0:1], 7, 6
	v_cmp_gt_u32_e64 s[4:5], 7, 5
	s_and_saveexec_b64 s[2:3], s[4:5]
	v_lshl_add_u32 v2, v1, 2, 0
	v_add_u32_e32 v2, 0x20000, v2
	v_mov_b32_e32 v3, 0
	ds_write_b32 v2, v3
	s_or_b64 exec, exec, s[2:3]
	s_and_saveexec_b64 s[2:3], s[0:1]
	s_add_i32 s0, 0, 0x20000
	v_lshl_add_u32 v1, v1, 2, s0
	v_mov_b32_e32 v2, 0
	ds_write_b32 v1, v2 offset:2048
	s_or_b64 exec, exec, s[2:3]
	s_waitcnt lgkmcnt(0)
	s_add_u32 s0, s48, 0x4000
	s_addc_u32 s1, s49, 0
	s_sub_i32 s2, s51, s50
	s_cmp_lt_i32 s2, 2
	s_mov_b32 s2, 0
	s_mov_b32 s46, 0
	v_cmp_eq_u32_e32 vcc, 0, v0
	v_writelane_b32 v254, s2, 5
	s_barrier
	s_cbranch_scc1 .LBB0_13
	s_getreg_b32 s2, hwreg(HW_REG_XCC_ID, 0, 4)
	s_and_b32 s46, s2, 15
	s_and_saveexec_b64 s[2:3], vcc
	s_cbranch_execz .LBB0_12
	s_mov_b64 s[4:5], exec
	v_mbcnt_lo_u32_b32 v1, s4, 0
	v_mbcnt_hi_u32_b32 v1, s5, v1
	v_cmp_eq_u32_e32 vcc, 0, v1
	s_and_b64 s[6:7], exec, vcc
	s_mov_b64 exec, s[6:7]
	s_cbranch_execz .LBB0_12
	s_lshl_b32 s6, s46, 8
	s_bcnt1_i32_b64 s4, s[4:5]
	v_mov_b32_e32 v1, s6
	v_mov_b32_e32 v2, s4
	global_atomic_add v1, v2, s[0:1] offset:1024

.LBB0_317:
	s_ashr_i32 s6, s6, 3
	s_add_i32 s6, s9, s6
	s_ashr_i32 s7, s6, 31
	s_lshr_b32 s7, s7, 26
	s_add_i32 s7, s6, s7
	s_ashr_i32 s9, s7, 6
	s_and_b32 s7, s7, 0xffc0
	s_sub_i32 s6, s6, s7
	s_bfe_i32 s7, s6, 0x80000
	s_bfe_u32 s7, s7, 0x3000c
	s_add_i32 s7, s6, s7
	s_bfe_i32 s10, s7, 0x80000
	s_and_b32 s7, s7, 0xf8
	s_sub_i32 s6, s6, s7
	s_sext_i32_i8 s6, s6
	s_sext_i32_i16 s10, s10
	s_ashr_i32 s100, s10, 3
	s_and_b32 vcc_lo, s100, 4
	s_lshl_b32 s100, s100, 1
	s_lshr_b32 vcc_hi, s6, 2
	s_or_b32 s100, s100, vcc_hi
	s_and_b32 s100, s100, 7
	s_and_b32 s6, s6, 3
	s_or_b32 s6, s6, vcc_lo
	s_lshl_b32 s10, s100, 3
	s_lshl_b32 s7, s9, 4
	s_lshl_b32 s6, s6, 1
	s_mov_b32 s13, 1
	s_add_i32 s9, s6, s7
	s_ashr_i32 s17, s10, 3
	s_mov_b32 s21, 0
	s_movk_i32 s11, 0x58
	s_mov_b64 s[36:37], 0
	s_mov_b64 s[40:41], -1
	s_mov_b32 s44, 0
	s_mov_b32 s23, 0

.LBB0_339:
	s_ashr_i32 s10, s10, 3
	s_add_i32 s10, s14, s10
	s_ashr_i32 s12, s10, 31
	s_lshr_b32 s12, s12, 26
	s_add_i32 s12, s10, s12
	s_ashr_i32 s14, s12, 6
	s_and_b32 s12, s12, 0xffc0
	s_sub_i32 s10, s10, s12
	s_bfe_i32 s12, s10, 0x80000
	s_bfe_u32 s12, s12, 0x3000c
	s_add_i32 s12, s10, s12
	s_bfe_i32 s15, s12, 0x80000
	s_and_b32 s12, s12, 0xf8
	s_sub_i32 s10, s10, s12
	s_sext_i32_i8 s10, s10
	s_sext_i32_i16 s15, s15
	s_ashr_i32 s100, s15, 3
	s_and_b32 vcc_lo, s100, 4
	s_lshl_b32 s100, s100, 1
	s_lshr_b32 vcc_hi, s10, 2
	s_or_b32 s100, s100, vcc_hi
	s_and_b32 s100, s100, 7
	s_and_b32 s10, s10, 3
	s_or_b32 s10, s10, vcc_lo
	s_lshl_b32 s15, s100, 3
	s_lshl_b32 s12, s14, 4
	s_lshl_b32 s10, s10, 1
	s_mov_b32 s22, 1
	s_add_i32 s16, s10, s12
	s_ashr_i32 s10, s15, 3
	s_movk_i32 s18, 0x58
	s_mov_b32 s60, 0
	s_mov_b64 s[64:65], -1
	s_mov_b32 s15, 0
	s_mov_b32 s14, 0
	s_mov_b32 s12, 0

.LBB0_962:
	s_sub_i32 s15, s73, 64
	s_max_i32 s74, s15, 0
	s_add_i32 s15, s9, 0x4000
	s_and_b32 s15, s15, 0x4000
	s_lshl_b64 s[16:17], s[74:75], 12
	v_lshl_add_u64 v[148:149], v[172:173], 0, s[16:17]
	s_add_i32 s18, s15, s10
	s_mov_b32 s19, m0
	s_mov_b32 m0, s18
	s_nop 0
	global_load_lds_dwordx4 v[148:149], off
	s_mov_b32 m0, s19
	v_lshl_add_u64 v[148:149], v[148:149], 0, v[66:67]
	s_addk_i32 s18, 0x400
	s_mov_b32 s19, m0
	s_mov_b32 m0, s18
	s_nop 0
	global_load_lds_dwordx4 v[148:149], off
	s_mov_b32 m0, s19
	v_lshl_add_u64 v[148:149], v[168:169], 0, s[16:17]
	s_add_i32 s15, s15, s11
	s_mov_b32 s16, m0
	s_mov_b32 m0, s15
	s_nop 0
	global_load_lds_dwordx4 v[148:149], off
	s_mov_b32 m0, s16
	s_mov_b64 s[16:17], 0x10000
	v_lshl_add_u64 v[148:149], v[148:149], 0, s[16:17]
	s_addk_i32 s15, 0x400
	s_mov_b32 s16, m0
	s_mov_b32 m0, s15
	s_nop 0
	global_load_lds_dwordx4 v[148:149], off
	s_mov_b32 m0, s16
.LBB0_963:
	s_cmp_lt_i32 s14, s12
	s_cbranch_scc1 .LBB0_981
	s_cmp_eq_u32 s12, s14
	s_cbranch_scc1 .Latt_gen_tile
	s_cmp_eq_u32 s78, s14
	s_cbranch_scc1 .Latt_gen_tile
	s_and_b32 s15, s9, 0x4000
	s_max_i32 s20, s73, 0
	v_or_b32_e32 v246, s15, v220
	v_xor_b32_e32 v250, 0x80, v246
	v_xor_b32_e32 v247, 32, v246
	v_xor_b32_e32 v248, 64, v246
	s_cmp_le_i32 s12, 1
	s_cbranch_scc1 .Latt_fast_b
	ds_read_b128 v[180:183], v250
	ds_read_b128 v[184:187], v219 offset:4096
	ds_read_b128 v[188:191], v246
	ds_read_b128 v[192:195], v219
	ds_read_b128 v[200:203], v247
	ds_read_b128 v[204:207], v219 offset:1024
	ds_read_b128 v[208:211], v248
	ds_read_b128 v[212:215], v219 offset:2048
	v_add_u32_e32 v148, s20, v216
	v_sub_u32_e32 v148, v148, v166
	v_cvt_f32_i32_e32 v148, v148
	v_fma_f32 v148, v164, v148, -v221
	v_add_f32_e32 v149, v164, v148
	v_add_f32_e32 v150, v176, v148
	v_add_f32_e32 v151, v177, v149
	v_add_f32_e32 v152, v174, v148
	v_add_f32_e32 v153, v175, v149
	v_add_f32_e32 v154, v174, v150
	v_add_f32_e32 v155, v175, v151
	v_add_f32_e32 v156, v174, v152
	v_add_f32_e32 v157, v175, v153
	v_add_f32_e32 v158, v174, v154
	v_add_f32_e32 v159, v175, v155
	v_add_f32_e32 v160, v174, v156
	v_add_f32_e32 v161, v175, v157
	v_add_f32_e32 v162, v174, v158
	v_add_f32_e32 v163, v175, v159
	v_xor_b32_e32 v249, 0x60, v246
	v_xor_b32_e32 v251, 0xa0, v246
	v_xor_b32_e32 v252, 0xc0, v246
	v_xor_b32_e32 v253, 0xe0, v246
	v_add_u32_e32 v228, s15, v222
	s_waitcnt lgkmcnt(6)
	v_mfma_f32_32x32x16_bf16 v[132:147], v[180:183], v[184:187], v[148:163]
	ds_read_b128 v[180:183], v249
	ds_read_b128 v[184:187], v219 offset:3072
	s_waitcnt lgkmcnt(6)
	v_mfma_f32_32x32x16_bf16 v[148:163], v[188:191], v[192:195], v[148:163]
	ds_read_b128 v[188:191], v251
	ds_read_b128 v[192:195], v219 offset:5120
	s_waitcnt lgkmcnt(6)
	v_mfma_f32_32x32x16_bf16 v[148:163], v[200:203], v[204:207], v[148:163]
	ds_read_b128 v[200:203], v252
	ds_read_b128 v[204:207], v219 offset:6144
	s_waitcnt lgkmcnt(6)
	v_mfma_f32_32x32x16_bf16 v[148:163], v[208:211], v[212:215], v[148:163]
	ds_read_b128 v[208:211], v253
	ds_read_b128 v[212:215], v219 offset:7168
	s_waitcnt lgkmcnt(6)
	v_mfma_f32_32x32x16_bf16 v[148:163], v[180:183], v[184:187], v[148:163]
	ds_read_b64_tr_b16 v[180:181], v228 offset:32768
	ds_read_b64_tr_b16 v[182:183], v228 offset:33280
	ds_read_b64_tr_b16 v[184:185], v228 offset:33792
	ds_read_b64_tr_b16 v[186:187], v228 offset:34304
	s_waitcnt lgkmcnt(8)
	v_mfma_f32_32x32x16_bf16 v[132:147], v[188:191], v[192:195], v[132:147]
	ds_read_b64_tr_b16 v[188:189], v228 offset:36864
	ds_read_b64_tr_b16 v[190:191], v228 offset:37376
	ds_read_b64_tr_b16 v[192:193], v228 offset:37888
	ds_read_b64_tr_b16 v[194:195], v228 offset:38400
	s_waitcnt lgkmcnt(10)
	v_mfma_f32_32x32x16_bf16 v[132:147], v[200:203], v[204:207], v[132:147]
	ds_read_b64_tr_b16 v[200:201], v228 offset:40960
	ds_read_b64_tr_b16 v[202:203], v228 offset:41472
	ds_read_b64_tr_b16 v[204:205], v228 offset:41984
	ds_read_b64_tr_b16 v[206:207], v228 offset:42496
	s_waitcnt lgkmcnt(12)
	v_mfma_f32_32x32x16_bf16 v[132:147], v[208:211], v[212:215], v[132:147]
	ds_read_b64_tr_b16 v[208:209], v228 offset:45056
	ds_read_b64_tr_b16 v[210:211], v228 offset:45568
	v_exp_f32_e32 v148, v148
	v_exp_f32_e32 v149, v149
	v_exp_f32_e32 v150, v150
	v_exp_f32_e32 v151, v151
	v_exp_f32_e32 v152, v152
	v_exp_f32_e32 v153, v153
	v_exp_f32_e32 v154, v154
	v_exp_f32_e32 v155, v155
	v_exp_f32_e32 v156, v156
	v_exp_f32_e32 v157, v157
	v_exp_f32_e32 v158, v158
	v_exp_f32_e32 v159, v159
	v_exp_f32_e32 v160, v160
	v_exp_f32_e32 v161, v161
	v_exp_f32_e32 v162, v162
	v_exp_f32_e32 v163, v163
	v_add_f32_e32 v170, v170, v148
	v_add_f32_e32 v171, v171, v149
	v_cvt_pk_bf16_f32 v230, v148, v149
	v_add_f32_e32 v170, v170, v150
	v_add_f32_e32 v171, v171, v151
	v_cvt_pk_bf16_f32 v231, v150, v151
	v_add_f32_e32 v170, v170, v152
	v_add_f32_e32 v171, v171, v153
	v_cvt_pk_bf16_f32 v232, v152, v153
	v_add_f32_e32 v170, v170, v154
	v_add_f32_e32 v171, v171, v155
	v_cvt_pk_bf16_f32 v233, v154, v155
	v_add_f32_e32 v170, v170, v156
	v_add_f32_e32 v171, v171, v157
	v_cvt_pk_bf16_f32 v234, v156, v157
	v_add_f32_e32 v170, v170, v158
	v_add_f32_e32 v171, v171, v159
	v_cvt_pk_bf16_f32 v235, v158, v159
	v_add_f32_e32 v170, v170, v160
	v_add_f32_e32 v171, v171, v161
	v_cvt_pk_bf16_f32 v236, v160, v161
	v_add_f32_e32 v170, v170, v162
	v_add_f32_e32 v171, v171, v163
	v_cvt_pk_bf16_f32 v237, v162, v163
	s_waitcnt lgkmcnt(12)
	ds_read_b64_tr_b16 v[212:213], v228 offset:46080
	ds_read_b64_tr_b16 v[214:215], v228 offset:46592
	v_mfma_f32_32x32x16_bf16 v[100:115], v[180:183], v[230:233], v[100:115]
	v_exp_f32_e32 v132, v132
	v_exp_f32_e32 v133, v133
	s_waitcnt lgkmcnt(12)
	v_mfma_f32_32x32x16_bf16 v[100:115], v[184:187], v[234:237], v[100:115]
	v_exp_f32_e32 v134, v134
	v_exp_f32_e32 v135, v135
	v_add_f32_e32 v178, v178, v132
	v_add_f32_e32 v179, v179, v133
	v_cvt_pk_bf16_f32 v238, v132, v133
	s_waitcnt lgkmcnt(10)
	v_mfma_f32_32x32x16_bf16 v[68:83], v[188:191], v[230:233], v[68:83]
	v_exp_f32_e32 v136, v136
	v_exp_f32_e32 v137, v137
	v_add_f32_e32 v178, v178, v134
	v_add_f32_e32 v179, v179, v135
	v_cvt_pk_bf16_f32 v239, v134, v135
	s_waitcnt lgkmcnt(8)
	v_mfma_f32_32x32x16_bf16 v[68:83], v[192:195], v[234:237], v[68:83]
	v_exp_f32_e32 v138, v138
	v_exp_f32_e32 v139, v139
	v_add_f32_e32 v178, v178, v136
	v_add_f32_e32 v179, v179, v137
	v_cvt_pk_bf16_f32 v240, v136, v137
	s_waitcnt lgkmcnt(6)
	v_mfma_f32_32x32x16_bf16 v[34:49], v[200:203], v[230:233], v[34:49]
	v_exp_f32_e32 v140, v140
	v_exp_f32_e32 v141, v141
	v_add_f32_e32 v178, v178, v138
	v_add_f32_e32 v179, v179, v139
	v_cvt_pk_bf16_f32 v241, v138, v139
	s_waitcnt lgkmcnt(4)
	v_mfma_f32_32x32x16_bf16 v[34:49], v[204:207], v[234:237], v[34:49]
	v_exp_f32_e32 v142, v142
	v_exp_f32_e32 v143, v143
	v_add_f32_e32 v178, v178, v140
	v_add_f32_e32 v179, v179, v141
	v_cvt_pk_bf16_f32 v242, v140, v141
	s_waitcnt lgkmcnt(2)
	v_mfma_f32_32x32x16_bf16 v[18:33], v[208:211], v[230:233], v[18:33]
	v_exp_f32_e32 v144, v144
	v_exp_f32_e32 v145, v145
	v_add_f32_e32 v178, v178, v142
	v_add_f32_e32 v179, v179, v143
	v_cvt_pk_bf16_f32 v243, v142, v143
	s_waitcnt lgkmcnt(0)
	v_mfma_f32_32x32x16_bf16 v[18:33], v[212:215], v[234:237], v[18:33]
	v_exp_f32_e32 v146, v146
	v_exp_f32_e32 v147, v147
	v_add_f32_e32 v178, v178, v144
	v_add_f32_e32 v179, v179, v145
	v_cvt_pk_bf16_f32 v244, v144, v145
	s_nop 0
	v_add_f32_e32 v178, v178, v146
	v_add_f32_e32 v179, v179, v147
	v_cvt_pk_bf16_f32 v245, v146, v147
	v_mfma_f32_32x32x16_bf16 v[116:131], v[180:183], v[238:241], v[116:131]
	v_add3_u32 v148, s20, v216, 32
	v_sub_u32_e32 v148, v148, v166
	v_mfma_f32_32x32x16_bf16 v[116:131], v[184:187], v[242:245], v[116:131]
	ds_read_b128 v[180:183], v250 offset:8192
	ds_read_b128 v[184:187], v219 offset:4096
	v_cvt_f32_i32_e32 v148, v148
	v_fma_f32 v148, v164, v148, -v221
	v_mfma_f32_32x32x16_bf16 v[84:99], v[188:191], v[238:241], v[84:99]
	v_add_f32_e32 v149, v164, v148
	v_add_f32_e32 v150, v176, v148
	v_add_f32_e32 v151, v177, v149
	v_mfma_f32_32x32x16_bf16 v[84:99], v[192:195], v[242:245], v[84:99]
	ds_read_b128 v[188:191], v246 offset:8192
	ds_read_b128 v[192:195], v219
	v_add_f32_e32 v152, v174, v148
	v_add_f32_e32 v153, v175, v149
	v_add_f32_e32 v154, v174, v150
	v_add_f32_e32 v155, v175, v151
	v_mfma_f32_32x32x16_bf16 v[50:65], v[200:203], v[238:241], v[50:65]
	v_add_f32_e32 v156, v174, v152
	v_add_f32_e32 v157, v175, v153
	v_add_f32_e32 v158, v174, v154
	v_add_f32_e32 v159, v175, v155
	v_mfma_f32_32x32x16_bf16 v[50:65], v[204:207], v[242:245], v[50:65]
	ds_read_b128 v[200:203], v247 offset:8192
	ds_read_b128 v[204:207], v219 offset:1024
	v_add_f32_e32 v160, v174, v156
	v_add_f32_e32 v161, v175, v157
	v_add_f32_e32 v162, v174, v158
	v_add_f32_e32 v163, v175, v159
	v_mfma_f32_32x32x16_bf16 v[2:17], v[208:211], v[238:241], v[2:17]
	v_mfma_f32_32x32x16_bf16 v[2:17], v[212:215], v[242:245], v[2:17]
	ds_read_b128 v[208:211], v248 offset:8192
	ds_read_b128 v[212:215], v219 offset:2048
	s_waitcnt lgkmcnt(6)
	v_mfma_f32_32x32x16_bf16 v[132:147], v[180:183], v[184:187], v[148:163]
	ds_read_b128 v[180:183], v249 offset:8192
	ds_read_b128 v[184:187], v219 offset:3072
	s_waitcnt lgkmcnt(6)
	v_mfma_f32_32x32x16_bf16 v[148:163], v[188:191], v[192:195], v[148:163]
	ds_read_b128 v[188:191], v251 offset:8192
	ds_read_b128 v[192:195], v219 offset:5120
	s_waitcnt lgkmcnt(6)
	v_mfma_f32_32x32x16_bf16 v[148:163], v[200:203], v[204:207], v[148:163]
	ds_read_b128 v[200:203], v252 offset:8192
	ds_read_b128 v[204:207], v219 offset:6144
	s_waitcnt lgkmcnt(6)
	v_mfma_f32_32x32x16_bf16 v[148:163], v[208:211], v[212:215], v[148:163]
	ds_read_b128 v[208:211], v253 offset:8192
	ds_read_b128 v[212:215], v219 offset:7168
	s_waitcnt lgkmcnt(6)
	v_mfma_f32_32x32x16_bf16 v[148:163], v[180:183], v[184:187], v[148:163]
	ds_read_b64_tr_b16 v[180:181], v228 offset:34816
	ds_read_b64_tr_b16 v[182:183], v228 offset:35328
	ds_read_b64_tr_b16 v[184:185], v228 offset:35840
	ds_read_b64_tr_b16 v[186:187], v228 offset:36352
	s_waitcnt lgkmcnt(8)
	v_mfma_f32_32x32x16_bf16 v[132:147], v[188:191], v[192:195], v[132:147]
	ds_read_b64_tr_b16 v[188:189], v228 offset:38912
	ds_read_b64_tr_b16 v[190:191], v228 offset:39424
	ds_read_b64_tr_b16 v[192:193], v228 offset:39936
	ds_read_b64_tr_b16 v[194:195], v228 offset:40448
	s_waitcnt lgkmcnt(10)
	v_mfma_f32_32x32x16_bf16 v[132:147], v[200:203], v[204:207], v[132:147]
	ds_read_b64_tr_b16 v[200:201], v228 offset:43008
	ds_read_b64_tr_b16 v[202:203], v228 offset:43520
	ds_read_b64_tr_b16 v[204:205], v228 offset:44032
	ds_read_b64_tr_b16 v[206:207], v228 offset:44544
	s_waitcnt lgkmcnt(12)
	v_mfma_f32_32x32x16_bf16 v[132:147], v[208:211], v[212:215], v[132:147]
	ds_read_b64_tr_b16 v[208:209], v228 offset:47104
	ds_read_b64_tr_b16 v[210:211], v228 offset:47616
	v_exp_f32_e32 v148, v148
	v_exp_f32_e32 v149, v149
	v_exp_f32_e32 v150, v150
	v_exp_f32_e32 v151, v151
	v_exp_f32_e32 v152, v152
	v_exp_f32_e32 v153, v153
	v_exp_f32_e32 v154, v154
	v_exp_f32_e32 v155, v155
	v_exp_f32_e32 v156, v156
	v_exp_f32_e32 v157, v157
	v_exp_f32_e32 v158, v158
	v_exp_f32_e32 v159, v159
	v_exp_f32_e32 v160, v160
	v_exp_f32_e32 v161, v161
	v_exp_f32_e32 v162, v162
	v_exp_f32_e32 v163, v163
	v_add_f32_e32 v170, v170, v148
	v_add_f32_e32 v171, v171, v149
	v_cvt_pk_bf16_f32 v230, v148, v149
	v_add_f32_e32 v170, v170, v150
	v_add_f32_e32 v171, v171, v151
	v_cvt_pk_bf16_f32 v231, v150, v151
	v_add_f32_e32 v170, v170, v152
	v_add_f32_e32 v171, v171, v153
	v_cvt_pk_bf16_f32 v232, v152, v153
	v_add_f32_e32 v170, v170, v154
	v_add_f32_e32 v171, v171, v155
	v_cvt_pk_bf16_f32 v233, v154, v155
	v_add_f32_e32 v170, v170, v156
	v_add_f32_e32 v171, v171, v157
	v_cvt_pk_bf16_f32 v234, v156, v157
	v_add_f32_e32 v170, v170, v158
	v_add_f32_e32 v171, v171, v159
	v_cvt_pk_bf16_f32 v235, v158, v159
	v_add_f32_e32 v170, v170, v160
	v_add_f32_e32 v171, v171, v161
	v_cvt_pk_bf16_f32 v236, v160, v161
	v_add_f32_e32 v170, v170, v162
	v_add_f32_e32 v171, v171, v163
	v_cvt_pk_bf16_f32 v237, v162, v163
	s_waitcnt lgkmcnt(12)
	ds_read_b64_tr_b16 v[212:213], v228 offset:48128
	ds_read_b64_tr_b16 v[214:215], v228 offset:48640
	v_mfma_f32_32x32x16_bf16 v[100:115], v[180:183], v[230:233], v[100:115]
	v_exp_f32_e32 v132, v132
	v_exp_f32_e32 v133, v133
	s_waitcnt lgkmcnt(12)
	v_mfma_f32_32x32x16_bf16 v[100:115], v[184:187], v[234:237], v[100:115]
	v_exp_f32_e32 v134, v134
	v_exp_f32_e32 v135, v135
	v_add_f32_e32 v178, v178, v132
	v_add_f32_e32 v179, v179, v133
	v_cvt_pk_bf16_f32 v238, v132, v133
	s_waitcnt lgkmcnt(10)
	v_mfma_f32_32x32x16_bf16 v[68:83], v[188:191], v[230:233], v[68:83]
	v_exp_f32_e32 v136, v136
	v_exp_f32_e32 v137, v137
	v_add_f32_e32 v178, v178, v134
	v_add_f32_e32 v179, v179, v135
	v_cvt_pk_bf16_f32 v239, v134, v135
	s_waitcnt lgkmcnt(8)
	v_mfma_f32_32x32x16_bf16 v[68:83], v[192:195], v[234:237], v[68:83]
	v_exp_f32_e32 v138, v138
	v_exp_f32_e32 v139, v139
	v_add_f32_e32 v178, v178, v136
	v_add_f32_e32 v179, v179, v137
	v_cvt_pk_bf16_f32 v240, v136, v137
	s_waitcnt lgkmcnt(6)
	v_mfma_f32_32x32x16_bf16 v[34:49], v[200:203], v[230:233], v[34:49]
	v_exp_f32_e32 v140, v140
	v_exp_f32_e32 v141, v141
	v_add_f32_e32 v178, v178, v138
	v_add_f32_e32 v179, v179, v139
	v_cvt_pk_bf16_f32 v241, v138, v139
	s_waitcnt lgkmcnt(4)
	v_mfma_f32_32x32x16_bf16 v[34:49], v[204:207], v[234:237], v[34:49]
	v_exp_f32_e32 v142, v142
	v_exp_f32_e32 v143, v143
	v_add_f32_e32 v178, v178, v140
	v_add_f32_e32 v179, v179, v141
	v_cvt_pk_bf16_f32 v242, v140, v141
	s_waitcnt lgkmcnt(2)
	v_mfma_f32_32x32x16_bf16 v[18:33], v[208:211], v[230:233], v[18:33]
	v_exp_f32_e32 v144, v144
	v_exp_f32_e32 v145, v145
	v_add_f32_e32 v178, v178, v142
	v_add_f32_e32 v179, v179, v143
	v_cvt_pk_bf16_f32 v243, v142, v143
	s_waitcnt lgkmcnt(0)
	v_mfma_f32_32x32x16_bf16 v[18:33], v[212:215], v[234:237], v[18:33]
	v_exp_f32_e32 v146, v146
	v_exp_f32_e32 v147, v147
	v_add_f32_e32 v178, v178, v144
	v_add_f32_e32 v179, v179, v145
	v_cvt_pk_bf16_f32 v244, v144, v145
	s_nop 0
	v_add_f32_e32 v178, v178, v146
	v_add_f32_e32 v179, v179, v147
	v_cvt_pk_bf16_f32 v245, v146, v147
	v_mfma_f32_32x32x16_bf16 v[116:131], v[180:183], v[238:241], v[116:131]
	v_mfma_f32_32x32x16_bf16 v[116:131], v[184:187], v[242:245], v[116:131]
	v_mfma_f32_32x32x16_bf16 v[84:99], v[188:191], v[238:241], v[84:99]
	v_mfma_f32_32x32x16_bf16 v[84:99], v[192:195], v[242:245], v[84:99]
	v_mfma_f32_32x32x16_bf16 v[50:65], v[200:203], v[238:241], v[50:65]
	v_mfma_f32_32x32x16_bf16 v[50:65], v[204:207], v[242:245], v[50:65]
	v_mfma_f32_32x32x16_bf16 v[2:17], v[208:211], v[238:241], v[2:17]
	v_mfma_f32_32x32x16_bf16 v[2:17], v[212:215], v[242:245], v[2:17]
	s_branch .LBB0_981
.Latt_fast_b:
	s_cmp_eq_u32 s101, 0
	s_cbranch_scc1 .Latt_b_cold
	v_xor_b32_e32 v249, 0x60, v246
	v_xor_b32_e32 v251, 0xa0, v246
	v_xor_b32_e32 v252, 0xc0, v246
	v_xor_b32_e32 v253, 0xe0, v246
	v_add_u32_e32 v228, s15, v222
	s_mov_b32 s101, 0
	v_mfma_f32_32x32x16_bf16 v[100:115], v[180:183], v[230:233], v[100:115]
	v_exp_f32_e32 v132, v132
	v_exp_f32_e32 v133, v133
	s_waitcnt lgkmcnt(12)
	v_mfma_f32_32x32x16_bf16 v[100:115], v[184:187], v[234:237], v[100:115]
	v_exp_f32_e32 v134, v134
	v_exp_f32_e32 v135, v135
	v_add_f32_e32 v178, v178, v132
	v_add_f32_e32 v179, v179, v133
	v_cvt_pk_bf16_f32 v238, v132, v133
	s_waitcnt lgkmcnt(10)
	v_mfma_f32_32x32x16_bf16 v[68:83], v[188:191], v[230:233], v[68:83]
	v_exp_f32_e32 v136, v136
	v_exp_f32_e32 v137, v137
	v_add_f32_e32 v178, v178, v134
	v_add_f32_e32 v179, v179, v135
	v_cvt_pk_bf16_f32 v239, v134, v135
	s_waitcnt lgkmcnt(8)
	v_mfma_f32_32x32x16_bf16 v[68:83], v[192:195], v[234:237], v[68:83]
	v_exp_f32_e32 v138, v138
	v_exp_f32_e32 v139, v139
	v_add_f32_e32 v178, v178, v136
	v_add_f32_e32 v179, v179, v137
	v_cvt_pk_bf16_f32 v240, v136, v137
	s_waitcnt lgkmcnt(6)
	v_mfma_f32_32x32x16_bf16 v[34:49], v[200:203], v[230:233], v[34:49]
	v_exp_f32_e32 v140, v140
	v_exp_f32_e32 v141, v141
	v_add_f32_e32 v178, v178, v138
	v_add_f32_e32 v179, v179, v139
	v_cvt_pk_bf16_f32 v241, v138, v139
	s_waitcnt lgkmcnt(4)
	v_mfma_f32_32x32x16_bf16 v[34:49], v[204:207], v[234:237], v[34:49]
	v_exp_f32_e32 v142, v142
	v_exp_f32_e32 v143, v143
	v_add_f32_e32 v178, v178, v140
	v_add_f32_e32 v179, v179, v141
	v_cvt_pk_bf16_f32 v242, v140, v141
	s_waitcnt lgkmcnt(2)
	v_mfma_f32_32x32x16_bf16 v[18:33], v[208:211], v[230:233], v[18:33]
	v_exp_f32_e32 v144, v144
	v_exp_f32_e32 v145, v145
	v_add_f32_e32 v178, v178, v142
	v_add_f32_e32 v179, v179, v143
	v_cvt_pk_bf16_f32 v243, v142, v143
	s_waitcnt lgkmcnt(0)
	v_mfma_f32_32x32x16_bf16 v[18:33], v[212:215], v[234:237], v[18:33]
	v_exp_f32_e32 v146, v146
	v_exp_f32_e32 v147, v147
	v_add_f32_e32 v178, v178, v144
	v_add_f32_e32 v179, v179, v145
	v_cvt_pk_bf16_f32 v244, v144, v145
	s_nop 0
	v_add_f32_e32 v178, v178, v146
	v_add_f32_e32 v179, v179, v147
	v_cvt_pk_bf16_f32 v245, v146, v147
	v_mfma_f32_32x32x16_bf16 v[116:131], v[180:183], v[238:241], v[116:131]
	v_add_u32_e32 v148, s20, v216
	v_sub_u32_e32 v148, v148, v166
	v_mfma_f32_32x32x16_bf16 v[116:131], v[184:187], v[242:245], v[116:131]
	ds_read_b128 v[180:183], v250
	ds_read_b128 v[184:187], v219 offset:4096
	v_cvt_f32_i32_e32 v148, v148
	v_fma_f32 v148, v164, v148, -v221
	v_mfma_f32_32x32x16_bf16 v[84:99], v[188:191], v[238:241], v[84:99]
	v_add_f32_e32 v149, v164, v148
	v_add_f32_e32 v150, v176, v148
	v_add_f32_e32 v151, v177, v149
	v_mfma_f32_32x32x16_bf16 v[84:99], v[192:195], v[242:245], v[84:99]
	ds_read_b128 v[188:191], v246
	ds_read_b128 v[192:195], v219
	v_add_f32_e32 v152, v174, v148
	v_add_f32_e32 v153, v175, v149
	v_add_f32_e32 v154, v174, v150
	v_add_f32_e32 v155, v175, v151
	v_mfma_f32_32x32x16_bf16 v[50:65], v[200:203], v[238:241], v[50:65]
	v_add_f32_e32 v156, v174, v152
	v_add_f32_e32 v157, v175, v153
	v_add_f32_e32 v158, v174, v154
	v_add_f32_e32 v159, v175, v155
	v_mfma_f32_32x32x16_bf16 v[50:65], v[204:207], v[242:245], v[50:65]
	ds_read_b128 v[200:203], v247
	ds_read_b128 v[204:207], v219 offset:1024
	v_add_f32_e32 v160, v174, v156
	v_add_f32_e32 v161, v175, v157
	v_add_f32_e32 v162, v174, v158
	v_add_f32_e32 v163, v175, v159
	v_mfma_f32_32x32x16_bf16 v[2:17], v[208:211], v[238:241], v[2:17]
	v_mfma_f32_32x32x16_bf16 v[2:17], v[212:215], v[242:245], v[2:17]
	ds_read_b128 v[208:211], v248
	ds_read_b128 v[212:215], v219 offset:2048
	s_branch .Latt_b_main
.Latt_b_cold:
	ds_read_b128 v[180:183], v250
	ds_read_b128 v[184:187], v219 offset:4096
	ds_read_b128 v[188:191], v246
	ds_read_b128 v[192:195], v219
	ds_read_b128 v[200:203], v247
	ds_read_b128 v[204:207], v219 offset:1024
	ds_read_b128 v[208:211], v248
	ds_read_b128 v[212:215], v219 offset:2048
	v_add_u32_e32 v148, s20, v216
	v_sub_u32_e32 v148, v148, v166
	v_cvt_f32_i32_e32 v148, v148
	v_fma_f32 v148, v164, v148, -v221
	v_add_f32_e32 v149, v164, v148
	v_add_f32_e32 v150, v176, v148
	v_add_f32_e32 v151, v177, v149
	v_add_f32_e32 v152, v174, v148
	v_add_f32_e32 v153, v175, v149
	v_add_f32_e32 v154, v174, v150
	v_add_f32_e32 v155, v175, v151
	v_add_f32_e32 v156, v174, v152
	v_add_f32_e32 v157, v175, v153
	v_add_f32_e32 v158, v174, v154
	v_add_f32_e32 v159, v175, v155
	v_add_f32_e32 v160, v174, v156
	v_add_f32_e32 v161, v175, v157
	v_add_f32_e32 v162, v174, v158
	v_add_f32_e32 v163, v175, v159
	v_xor_b32_e32 v249, 0x60, v246
	v_xor_b32_e32 v251, 0xa0, v246
	v_xor_b32_e32 v252, 0xc0, v246
	v_xor_b32_e32 v253, 0xe0, v246
	v_add_u32_e32 v228, s15, v222
.Latt_b_main:
	s_waitcnt lgkmcnt(6)
	v_mfma_f32_32x32x16_bf16 v[132:147], v[180:183], v[184:187], v[148:163]
	ds_read_b128 v[180:183], v249
	ds_read_b128 v[184:187], v219 offset:3072
	s_waitcnt lgkmcnt(6)
	v_mfma_f32_32x32x16_bf16 v[148:163], v[188:191], v[192:195], v[148:163]
	ds_read_b128 v[188:191], v251
	ds_read_b128 v[192:195], v219 offset:5120
	s_waitcnt lgkmcnt(6)
	v_mfma_f32_32x32x16_bf16 v[148:163], v[200:203], v[204:207], v[148:163]
	ds_read_b128 v[200:203], v252
	ds_read_b128 v[204:207], v219 offset:6144
	s_waitcnt lgkmcnt(6)
	v_mfma_f32_32x32x16_bf16 v[148:163], v[208:211], v[212:215], v[148:163]
	ds_read_b128 v[208:211], v253
	ds_read_b128 v[212:215], v219 offset:7168
	s_waitcnt lgkmcnt(6)
	v_mfma_f32_32x32x16_bf16 v[148:163], v[180:183], v[184:187], v[148:163]
	ds_read_b64_tr_b16 v[180:181], v228 offset:32768
	ds_read_b64_tr_b16 v[182:183], v228 offset:33280
	ds_read_b64_tr_b16 v[184:185], v228 offset:33792
	ds_read_b64_tr_b16 v[186:187], v228 offset:34304
	s_waitcnt lgkmcnt(8)
	v_mfma_f32_32x32x16_bf16 v[132:147], v[188:191], v[192:195], v[132:147]
	ds_read_b64_tr_b16 v[188:189], v228 offset:36864
	ds_read_b64_tr_b16 v[190:191], v228 offset:37376
	ds_read_b64_tr_b16 v[192:193], v228 offset:37888
	ds_read_b64_tr_b16 v[194:195], v228 offset:38400
	s_waitcnt lgkmcnt(10)
	v_mfma_f32_32x32x16_bf16 v[132:147], v[200:203], v[204:207], v[132:147]
	ds_read_b64_tr_b16 v[200:201], v228 offset:40960
	ds_read_b64_tr_b16 v[202:203], v228 offset:41472
	ds_read_b64_tr_b16 v[204:205], v228 offset:41984
	ds_read_b64_tr_b16 v[206:207], v228 offset:42496
	s_waitcnt lgkmcnt(12)
	v_mfma_f32_32x32x16_bf16 v[132:147], v[208:211], v[212:215], v[132:147]
	ds_read_b64_tr_b16 v[208:209], v228 offset:45056
	ds_read_b64_tr_b16 v[210:211], v228 offset:45568
	v_exp_f32_e32 v148, v148
	v_exp_f32_e32 v149, v149
	v_exp_f32_e32 v150, v150
	v_exp_f32_e32 v151, v151
	v_exp_f32_e32 v152, v152
	v_exp_f32_e32 v153, v153
	v_exp_f32_e32 v154, v154
	v_exp_f32_e32 v155, v155
	v_exp_f32_e32 v156, v156
	v_exp_f32_e32 v157, v157
	v_exp_f32_e32 v158, v158
	v_exp_f32_e32 v159, v159
	v_exp_f32_e32 v160, v160
	v_exp_f32_e32 v161, v161
	v_exp_f32_e32 v162, v162
	v_exp_f32_e32 v163, v163
	v_add_f32_e32 v170, v170, v148
	v_add_f32_e32 v171, v171, v149
	v_cvt_pk_bf16_f32 v230, v148, v149
	v_add_f32_e32 v170, v170, v150
	v_add_f32_e32 v171, v171, v151
	v_cvt_pk_bf16_f32 v231, v150, v151
	v_add_f32_e32 v170, v170, v152
	v_add_f32_e32 v171, v171, v153
	v_cvt_pk_bf16_f32 v232, v152, v153
	v_add_f32_e32 v170, v170, v154
	v_add_f32_e32 v171, v171, v155
	v_cvt_pk_bf16_f32 v233, v154, v155
	v_add_f32_e32 v170, v170, v156
	v_add_f32_e32 v171, v171, v157
	v_cvt_pk_bf16_f32 v234, v156, v157
	v_add_f32_e32 v170, v170, v158
	v_add_f32_e32 v171, v171, v159
	v_cvt_pk_bf16_f32 v235, v158, v159
	v_add_f32_e32 v170, v170, v160
	v_add_f32_e32 v171, v171, v161
	v_cvt_pk_bf16_f32 v236, v160, v161
	v_add_f32_e32 v170, v170, v162
	v_add_f32_e32 v171, v171, v163
	v_cvt_pk_bf16_f32 v237, v162, v163
	s_waitcnt lgkmcnt(12)
	ds_read_b64_tr_b16 v[212:213], v228 offset:46080
	ds_read_b64_tr_b16 v[214:215], v228 offset:46592
	v_mfma_f32_32x32x16_bf16 v[100:115], v[180:183], v[230:233], v[100:115]
	v_exp_f32_e32 v132, v132
	v_exp_f32_e32 v133, v133
	s_waitcnt lgkmcnt(12)
	v_mfma_f32_32x32x16_bf16 v[100:115], v[184:187], v[234:237], v[100:115]
	v_exp_f32_e32 v134, v134
	v_exp_f32_e32 v135, v135
	v_add_f32_e32 v178, v178, v132
	v_add_f32_e32 v179, v179, v133
	v_cvt_pk_bf16_f32 v238, v132, v133
	s_waitcnt lgkmcnt(10)
	v_mfma_f32_32x32x16_bf16 v[68:83], v[188:191], v[230:233], v[68:83]
	v_exp_f32_e32 v136, v136
	v_exp_f32_e32 v137, v137
	v_add_f32_e32 v178, v178, v134
	v_add_f32_e32 v179, v179, v135
	v_cvt_pk_bf16_f32 v239, v134, v135
	s_waitcnt lgkmcnt(8)
	v_mfma_f32_32x32x16_bf16 v[68:83], v[192:195], v[234:237], v[68:83]
	v_exp_f32_e32 v138, v138
	v_exp_f32_e32 v139, v139
	v_add_f32_e32 v178, v178, v136
	v_add_f32_e32 v179, v179, v137
	v_cvt_pk_bf16_f32 v240, v136, v137
	s_waitcnt lgkmcnt(6)
	v_mfma_f32_32x32x16_bf16 v[34:49], v[200:203], v[230:233], v[34:49]
	v_exp_f32_e32 v140, v140
	v_exp_f32_e32 v141, v141
	v_add_f32_e32 v178, v178, v138
	v_add_f32_e32 v179, v179, v139
	v_cvt_pk_bf16_f32 v241, v138, v139
	s_waitcnt lgkmcnt(4)
	v_mfma_f32_32x32x16_bf16 v[34:49], v[204:207], v[234:237], v[34:49]
	v_exp_f32_e32 v142, v142
	v_exp_f32_e32 v143, v143
	v_add_f32_e32 v178, v178, v140
	v_add_f32_e32 v179, v179, v141
	v_cvt_pk_bf16_f32 v242, v140, v141
	s_waitcnt lgkmcnt(2)
	v_mfma_f32_32x32x16_bf16 v[18:33], v[208:211], v[230:233], v[18:33]
	v_exp_f32_e32 v144, v144
	v_exp_f32_e32 v145, v145
	v_add_f32_e32 v178, v178, v142
	v_add_f32_e32 v179, v179, v143
	v_cvt_pk_bf16_f32 v243, v142, v143
	s_waitcnt lgkmcnt(0)
	v_mfma_f32_32x32x16_bf16 v[18:33], v[212:215], v[234:237], v[18:33]
	v_exp_f32_e32 v146, v146
	v_exp_f32_e32 v147, v147
	v_add_f32_e32 v178, v178, v144
	v_add_f32_e32 v179, v179, v145
	v_cvt_pk_bf16_f32 v244, v144, v145
	s_nop 0
	v_add_f32_e32 v178, v178, v146
	v_add_f32_e32 v179, v179, v147
	v_cvt_pk_bf16_f32 v245, v146, v147
	v_mfma_f32_32x32x16_bf16 v[116:131], v[180:183], v[238:241], v[116:131]
	v_add3_u32 v148, s20, v216, 32
	v_sub_u32_e32 v148, v148, v166
	v_mfma_f32_32x32x16_bf16 v[116:131], v[184:187], v[242:245], v[116:131]
	ds_read_b128 v[180:183], v250 offset:8192
	ds_read_b128 v[184:187], v219 offset:4096
	v_cvt_f32_i32_e32 v148, v148
	v_fma_f32 v148, v164, v148, -v221
	v_mfma_f32_32x32x16_bf16 v[84:99], v[188:191], v[238:241], v[84:99]
	v_add_f32_e32 v149, v164, v148
	v_add_f32_e32 v150, v176, v148
	v_add_f32_e32 v151, v177, v149
	v_mfma_f32_32x32x16_bf16 v[84:99], v[192:195], v[242:245], v[84:99]
	ds_read_b128 v[188:191], v246 offset:8192
	ds_read_b128 v[192:195], v219
	v_add_f32_e32 v152, v174, v148
	v_add_f32_e32 v153, v175, v149
	v_add_f32_e32 v154, v174, v150
	v_add_f32_e32 v155, v175, v151
	v_mfma_f32_32x32x16_bf16 v[50:65], v[200:203], v[238:241], v[50:65]
	v_add_f32_e32 v156, v174, v152
	v_add_f32_e32 v157, v175, v153
	v_add_f32_e32 v158, v174, v154
	v_add_f32_e32 v159, v175, v155
	v_mfma_f32_32x32x16_bf16 v[50:65], v[204:207], v[242:245], v[50:65]
	ds_read_b128 v[200:203], v247 offset:8192
	ds_read_b128 v[204:207], v219 offset:1024
	v_add_f32_e32 v160, v174, v156
	v_add_f32_e32 v161, v175, v157
	v_add_f32_e32 v162, v174, v158
	v_add_f32_e32 v163, v175, v159
	v_mfma_f32_32x32x16_bf16 v[2:17], v[208:211], v[238:241], v[2:17]
	v_mfma_f32_32x32x16_bf16 v[2:17], v[212:215], v[242:245], v[2:17]
	ds_read_b128 v[208:211], v248 offset:8192
	ds_read_b128 v[212:215], v219 offset:2048
	s_waitcnt lgkmcnt(6)
	v_mfma_f32_32x32x16_bf16 v[132:147], v[180:183], v[184:187], v[148:163]
	ds_read_b128 v[180:183], v249 offset:8192
	ds_read_b128 v[184:187], v219 offset:3072
	s_waitcnt lgkmcnt(6)
	v_mfma_f32_32x32x16_bf16 v[148:163], v[188:191], v[192:195], v[148:163]
	ds_read_b128 v[188:191], v251 offset:8192
	ds_read_b128 v[192:195], v219 offset:5120
	s_waitcnt lgkmcnt(6)
	v_mfma_f32_32x32x16_bf16 v[148:163], v[200:203], v[204:207], v[148:163]
	ds_read_b128 v[200:203], v252 offset:8192
	ds_read_b128 v[204:207], v219 offset:6144
	s_waitcnt lgkmcnt(6)
	v_mfma_f32_32x32x16_bf16 v[148:163], v[208:211], v[212:215], v[148:163]
	ds_read_b128 v[208:211], v253 offset:8192
	ds_read_b128 v[212:215], v219 offset:7168
	s_waitcnt lgkmcnt(6)
	v_mfma_f32_32x32x16_bf16 v[148:163], v[180:183], v[184:187], v[148:163]
	ds_read_b64_tr_b16 v[180:181], v228 offset:34816
	ds_read_b64_tr_b16 v[182:183], v228 offset:35328
	ds_read_b64_tr_b16 v[184:185], v228 offset:35840
	ds_read_b64_tr_b16 v[186:187], v228 offset:36352
	s_waitcnt lgkmcnt(8)
	v_mfma_f32_32x32x16_bf16 v[132:147], v[188:191], v[192:195], v[132:147]
	ds_read_b64_tr_b16 v[188:189], v228 offset:38912
	ds_read_b64_tr_b16 v[190:191], v228 offset:39424
	ds_read_b64_tr_b16 v[192:193], v228 offset:39936
	ds_read_b64_tr_b16 v[194:195], v228 offset:40448
	s_waitcnt lgkmcnt(10)
	v_mfma_f32_32x32x16_bf16 v[132:147], v[200:203], v[204:207], v[132:147]
	ds_read_b64_tr_b16 v[200:201], v228 offset:43008
	ds_read_b64_tr_b16 v[202:203], v228 offset:43520
	ds_read_b64_tr_b16 v[204:205], v228 offset:44032
	ds_read_b64_tr_b16 v[206:207], v228 offset:44544
	s_waitcnt lgkmcnt(12)
	v_mfma_f32_32x32x16_bf16 v[132:147], v[208:211], v[212:215], v[132:147]
	ds_read_b64_tr_b16 v[208:209], v228 offset:47104
	ds_read_b64_tr_b16 v[210:211], v228 offset:47616
	v_exp_f32_e32 v148, v148
	v_exp_f32_e32 v149, v149
	v_exp_f32_e32 v150, v150
	v_exp_f32_e32 v151, v151
	v_exp_f32_e32 v152, v152
	v_exp_f32_e32 v153, v153
	v_exp_f32_e32 v154, v154
	v_exp_f32_e32 v155, v155
	v_exp_f32_e32 v156, v156
	v_exp_f32_e32 v157, v157
	v_exp_f32_e32 v158, v158
	v_exp_f32_e32 v159, v159
	v_exp_f32_e32 v160, v160
	v_exp_f32_e32 v161, v161
	v_exp_f32_e32 v162, v162
	v_exp_f32_e32 v163, v163
	v_add_f32_e32 v170, v170, v148
	v_add_f32_e32 v171, v171, v149
	v_cvt_pk_bf16_f32 v230, v148, v149
	v_add_f32_e32 v170, v170, v150
	v_add_f32_e32 v171, v171, v151
	v_cvt_pk_bf16_f32 v231, v150, v151
	v_add_f32_e32 v170, v170, v152
	v_add_f32_e32 v171, v171, v153
	v_cvt_pk_bf16_f32 v232, v152, v153
	v_add_f32_e32 v170, v170, v154
	v_add_f32_e32 v171, v171, v155
	v_cvt_pk_bf16_f32 v233, v154, v155
	v_add_f32_e32 v170, v170, v156
	v_add_f32_e32 v171, v171, v157
	v_cvt_pk_bf16_f32 v234, v156, v157
	v_add_f32_e32 v170, v170, v158
	v_add_f32_e32 v171, v171, v159
	v_cvt_pk_bf16_f32 v235, v158, v159
	v_add_f32_e32 v170, v170, v160
	v_add_f32_e32 v171, v171, v161
	v_cvt_pk_bf16_f32 v236, v160, v161
	v_add_f32_e32 v170, v170, v162
	v_add_f32_e32 v171, v171, v163
	v_cvt_pk_bf16_f32 v237, v162, v163
	s_waitcnt lgkmcnt(12)
	ds_read_b64_tr_b16 v[212:213], v228 offset:48128
	ds_read_b64_tr_b16 v[214:215], v228 offset:48640
	s_cmp_ge_i32 s13, s77
	s_cbranch_scc1 .Latt_b_flush
	s_cmp_eq_u32 s13, s78
	s_cbranch_scc1 .Latt_b_flush
	s_mov_b32 s101, 1
	s_branch .LBB0_981
.Latt_b_flush:
	v_mfma_f32_32x32x16_bf16 v[100:115], v[180:183], v[230:233], v[100:115]
	v_exp_f32_e32 v132, v132
	v_exp_f32_e32 v133, v133
	s_waitcnt lgkmcnt(12)
	v_mfma_f32_32x32x16_bf16 v[100:115], v[184:187], v[234:237], v[100:115]
	v_exp_f32_e32 v134, v134
	v_exp_f32_e32 v135, v135
	v_add_f32_e32 v178, v178, v132
	v_add_f32_e32 v179, v179, v133
	v_cvt_pk_bf16_f32 v238, v132, v133
	s_waitcnt lgkmcnt(10)
	v_mfma_f32_32x32x16_bf16 v[68:83], v[188:191], v[230:233], v[68:83]
	v_exp_f32_e32 v136, v136
	v_exp_f32_e32 v137, v137
	v_add_f32_e32 v178, v178, v134
	v_add_f32_e32 v179, v179, v135
	v_cvt_pk_bf16_f32 v239, v134, v135
	s_waitcnt lgkmcnt(8)
	v_mfma_f32_32x32x16_bf16 v[68:83], v[192:195], v[234:237], v[68:83]
	v_exp_f32_e32 v138, v138
	v_exp_f32_e32 v139, v139
	v_add_f32_e32 v178, v178, v136
	v_add_f32_e32 v179, v179, v137
	v_cvt_pk_bf16_f32 v240, v136, v137
	s_waitcnt lgkmcnt(6)
	v_mfma_f32_32x32x16_bf16 v[34:49], v[200:203], v[230:233], v[34:49]
	v_exp_f32_e32 v140, v140
	v_exp_f32_e32 v141, v141
	v_add_f32_e32 v178, v178, v138
	v_add_f32_e32 v179, v179, v139
	v_cvt_pk_bf16_f32 v241, v138, v139
	s_waitcnt lgkmcnt(4)
	v_mfma_f32_32x32x16_bf16 v[34:49], v[204:207], v[234:237], v[34:49]
	v_exp_f32_e32 v142, v142
	v_exp_f32_e32 v143, v143
	v_add_f32_e32 v178, v178, v140
	v_add_f32_e32 v179, v179, v141
	v_cvt_pk_bf16_f32 v242, v140, v141
	s_waitcnt lgkmcnt(2)
	v_mfma_f32_32x32x16_bf16 v[18:33], v[208:211], v[230:233], v[18:33]
	v_exp_f32_e32 v144, v144
	v_exp_f32_e32 v145, v145
	v_add_f32_e32 v178, v178, v142
	v_add_f32_e32 v179, v179, v143
	v_cvt_pk_bf16_f32 v243, v142, v143
	s_waitcnt lgkmcnt(0)
	v_mfma_f32_32x32x16_bf16 v[18:33], v[212:215], v[234:237], v[18:33]
	v_exp_f32_e32 v146, v146
	v_exp_f32_e32 v147, v147
	v_add_f32_e32 v178, v178, v144
	v_add_f32_e32 v179, v179, v145
	v_cvt_pk_bf16_f32 v244, v144, v145
	s_nop 0
	v_add_f32_e32 v178, v178, v146
	v_add_f32_e32 v179, v179, v147
	v_cvt_pk_bf16_f32 v245, v146, v147
	v_mfma_f32_32x32x16_bf16 v[116:131], v[180:183], v[238:241], v[116:131]
	v_mfma_f32_32x32x16_bf16 v[116:131], v[184:187], v[242:245], v[116:131]
	v_mfma_f32_32x32x16_bf16 v[84:99], v[188:191], v[238:241], v[84:99]
	v_mfma_f32_32x32x16_bf16 v[84:99], v[192:195], v[242:245], v[84:99]
	v_mfma_f32_32x32x16_bf16 v[50:65], v[200:203], v[238:241], v[50:65]
	v_mfma_f32_32x32x16_bf16 v[50:65], v[204:207], v[242:245], v[50:65]
	v_mfma_f32_32x32x16_bf16 v[2:17], v[208:211], v[238:241], v[2:17]
	v_mfma_f32_32x32x16_bf16 v[2:17], v[212:215], v[242:245], v[2:17]
	s_branch .LBB0_981

	.amdhsa_kernel _Z10fwd_kernel4Args
		.amdhsa_group_segment_fixed_size 0
		.amdhsa_private_segment_fixed_size 0
		.amdhsa_kernarg_size 504
		.amdhsa_user_sgpr_count 2
		.amdhsa_user_sgpr_dispatch_ptr 0
		.amdhsa_user_sgpr_queue_ptr 0
		.amdhsa_user_sgpr_kernarg_segment_ptr 1
		.amdhsa_user_sgpr_dispatch_id 0
		.amdhsa_user_sgpr_kernarg_preload_length 0
		.amdhsa_user_sgpr_kernarg_preload_offset 0
		.amdhsa_user_sgpr_private_segment_size 0
		.amdhsa_uses_dynamic_stack 0
		.amdhsa_enable_private_segment 0
		.amdhsa_system_sgpr_workgroup_id_x 1
		.amdhsa_system_sgpr_workgroup_id_y 0
		.amdhsa_system_sgpr_workgroup_id_z 0
		.amdhsa_system_sgpr_workgroup_info 0
		.amdhsa_system_vgpr_workitem_id 0
		.amdhsa_next_free_vgpr 256
		.amdhsa_next_free_sgpr 102
		.amdhsa_accum_offset 256
		.amdhsa_reserve_vcc 1
		.amdhsa_float_round_mode_32 0
		.amdhsa_float_round_mode_16_64 0
		.amdhsa_float_denorm_mode_32 3
		.amdhsa_float_denorm_mode_16_64 3
		.amdhsa_dx10_clamp 1
		.amdhsa_ieee_mode 1
		.amdhsa_fp16_overflow 0
		.amdhsa_tg_split 0
		.amdhsa_exception_fp_ieee_invalid_op 0
		.amdhsa_exception_fp_denorm_src 0
		.amdhsa_exception_fp_ieee_div_zero 0
		.amdhsa_exception_fp_ieee_overflow 0
		.amdhsa_exception_fp_ieee_underflow 0
		.amdhsa_exception_fp_ieee_inexact 0
		.amdhsa_exception_int_div_zero 0
	.end_amdhsa_kernel

amdhsa.kernels:
  - .agpr_count:     0
    .args:
      - .offset:         0
        .size:           248
        .value_kind:     by_value
      - .offset:         248
        .size:           4
        .value_kind:     hidden_block_count_x
      - .offset:         252
        .size:           4
        .value_kind:     hidden_block_count_y
      - .offset:         256
        .size:           4
        .value_kind:     hidden_block_count_z
      - .offset:         260
        .size:           2
        .value_kind:     hidden_group_size_x
      - .offset:         262
        .size:           2
        .value_kind:     hidden_group_size_y
      - .offset:         264
        .size:           2
        .value_kind:     hidden_group_size_z
      - .offset:         266
        .size:           2
        .value_kind:     hidden_remainder_x
      - .offset:         268
        .size:           2
        .value_kind:     hidden_remainder_y
      - .offset:         270
        .size:           2
        .value_kind:     hidden_remainder_z
      - .offset:         288
        .size:           8
        .value_kind:     hidden_global_offset_x
      - .offset:         296
        .size:           8
        .value_kind:     hidden_global_offset_y
      - .offset:         304
        .size:           8
        .value_kind:     hidden_global_offset_z
      - .offset:         312
        .size:           2
        .value_kind:     hidden_grid_dims
      - .offset:         368
        .size:           4
        .value_kind:     hidden_dynamic_lds_size
    .group_segment_fixed_size: 0
    .kernarg_segment_align: 8
    .kernarg_segment_size: 504
    .language:       OpenCL C
    .language_version:
      - 2
      - 0
    .max_flat_workgroup_size: 512
    .name:           _Z10fwd_kernel4Args
    .private_segment_fixed_size: 0
    .sgpr_count:     108
    .sgpr_spill_count: 125
    .symbol:         _Z10fwd_kernel4Args.kd
    .uniform_work_group_size: 1
    .uses_dynamic_stack: false
    .vgpr_count:     256
    .vgpr_spill_count: 0
    .wavefront_size: 64
